# P4c head-norm loop: next iteration's six loads issued one iteration ahead (top wait vmcnt(2) leaves the two ZA stores in flight)
# speedup vs baseline: 1.0015x; 1.0015x over previous
; #define GAS __attribute__((address_space(1)))
; __device__ __forceinline__ const float* kin(int k) { KArgs p = (KArgs)__builtin_amdgcn_kernarg_segment_ptr(); asm volatile("" : "+s"(p)); return p->in[k]; }
; __global__ void __launch_bounds__(NWAVES * 64, 2) mk_fwd(Args args) {
;     ...
;         const float* Og = (const float*)(ws + WS_XN); const bf16* OGb = (const bf16*)(ws + WS_OG); bf16* ZA = (bf16*)(ws + WS_ZA);
;         const float* gh = kin(12);
;         const int hl = F.lane & 31, hw = F.lane >> 5, c0 = 16 * hl;
;         f32x4 gg[4];
; #pragma unroll
;         for (int j = 0; j < 4; ++j) gg[j] = *(const GAS f32x4*)(gh + c0 + 4 * j);
;         for (int t = 2 * GW_ + hw; t < T; t += 2 * NGW) {
;             const size_t e = (size_t)t * DA + c0;
;             f32x4 o[4]; v4u og[2];
; #pragma unroll
;             for (int j = 0; j < 4; ++j) o[j] = NTL((const GAS f32x4*)(Og + e + 4 * j));
;             og[0] = NTL((const GAS v4u*)(OGb + e)); og[1] = NTL((const GAS v4u*)(OGb + e + 8));
;             float ss = 0.f;
; #pragma unroll
;             for (int j = 0; j < 4; ++j) ss += (o[j].x * o[j].x + o[j].y * o[j].y) + (o[j].z * o[j].z + o[j].w * o[j].w);
;             ss += __shfl_xor(ss, 1); ss += __shfl_xor(ss, 2); ss += __shfl_xor(ss, 4);
;             const float rstd = 1.f / sqrtf(ss * (1.f / 128.f) + EPS);
.LBB0_923:
	s_lshl_b32 s3, s33, 4
	s_lshl_b32 s8, s50, 1
	v_lshrrev_b32_e32 v1, 5, v189
	s_add_i32 s8, s8, s3
	s_waitcnt vmcnt(7)
	v_or_b32_e32 v18, s8, v1
	s_movk_i32 s3, 0x4400
	s_mov_b64 s[6:7], s[0:1]
	v_cmp_gt_i32_e32 vcc, s3, v18
	s_and_saveexec_b64 s[8:9], vcc
	s_cbranch_execz .LBB0_926
	s_load_dwordx2 s[6:7], s[6:7], 0x60
	v_lshlrev_b32_e32 v1, 6, v189
	v_and_b32_e32 v1, 0x7c0, v1
	s_lshl_b32 s10, s18, 4
	v_and_b32_e32 v26, 31, v189
	s_waitcnt lgkmcnt(0)
	global_load_dwordx4 v[2:5], v1, s[6:7] offset:48
	global_load_dwordx4 v[6:9], v1, s[6:7] offset:32
	global_load_dwordx4 v[10:13], v1, s[6:7] offset:16
	global_load_dwordx4 v[14:17], v1, s[6:7]
	v_mbcnt_lo_u32_b32 v1, -1, 0
	v_mbcnt_hi_u32_b32 v19, -1, v1
	v_and_b32_e32 v20, 64, v19
	v_xor_b32_e32 v1, 1, v19
	v_add_u32_e32 v20, 64, v20
	v_cmp_lt_i32_e32 vcc, v1, v20
	v_xor_b32_e32 v21, 2, v19
	s_ashr_i32 s11, s10, 31
	v_cndmask_b32_e32 v1, v19, v1, vcc
	v_cmp_lt_i32_e32 vcc, v21, v20
	v_lshlrev_b32_e32 v1, 2, v1
	s_lshl_b64 s[12:13], s[10:11], 10
	v_cndmask_b32_e32 v21, v19, v21, vcc
	v_lshlrev_b32_e32 v24, 2, v21
	v_xor_b32_e32 v21, 4, v19
	v_cmp_lt_i32_e32 vcc, v21, v20
	s_lshl_b64 s[14:15], s[10:11], 11
	s_mov_b64 s[16:17], 0
	v_cndmask_b32_e32 v19, v19, v21, vcc
	v_lshlrev_b32_e32 v25, 2, v19
	v_ashrrev_i32_e32 v19, 31, v18
	v_lshlrev_b64 v[20:21], 10, v[18:19]
	v_lshlrev_b64 v[22:23], 11, v[18:19]
	v_lshl_or_b32 v20, v26, 5, v20
	v_lshl_or_b32 v22, v26, 6, v22
	s_mov_b64 s[36:37], 0x2080000
	s_mov_b64 s[38:39], 0x8680000
	s_mov_b32 s3, 0x8680000
	v_mov_b32_e32 v19, 0x358637bd
	s_mov_b32 s11, 0xf800000
	v_mov_b32_e32 v26, 0x260
	s_mov_b32 s19, 0xb980000
	s_movk_i32 s40, 0x43ff
	s_mov_b32 s98, 0xb980000
	s_mov_b32 s99, 0
	v_lshl_add_u64 v[224:225], s[22:23], 0, v[22:23]
	v_lshl_add_u64 v[224:225], v[224:225], 0, s[36:37]
	global_load_dwordx4 v[200:203], v[224:225], off offset:32
	global_load_dwordx4 v[204:207], v[224:225], off offset:16
	global_load_dwordx4 v[208:211], v[224:225], off
	global_load_dwordx4 v[212:215], v[224:225], off offset:48
	v_lshl_add_u64 v[226:227], s[22:23], 0, v[20:21]
	v_lshl_add_u64 v[226:227], v[226:227], 0, s[38:39]
	global_load_dwordx4 v[216:219], v[226:227], off
	global_load_dwordx4 v[220:223], v[226:227], off offset:16
	s_waitcnt vmcnt(0)
; #define GAS __attribute__((address_space(1)))
; __device__ __forceinline__ unsigned pk2(float lo, float hi) { const f32x2_t_ v = {lo, hi}; return __builtin_bit_cast(unsigned, __builtin_convertvector(v, bf16x2_t_)); }
; __global__ void __launch_bounds__(NWAVES * 64, 2) mk_fwd(Args args) {
;     ...
;         for (int t = 2 * GW_ + hw; t < T; t += 2 * NGW) {
;             const size_t e = (size_t)t * DA + c0;
;             f32x4 o[4]; v4u og[2];
; #pragma unroll
;             for (int j = 0; j < 4; ++j) o[j] = NTL((const GAS f32x4*)(Og + e + 4 * j));
;             og[0] = NTL((const GAS v4u*)(OGb + e)); og[1] = NTL((const GAS v4u*)(OGb + e + 8));
;             float ss = 0.f;
; #pragma unroll
;             for (int j = 0; j < 4; ++j) ss += (o[j].x * o[j].x + o[j].y * o[j].y) + (o[j].z * o[j].z + o[j].w * o[j].w);
;             ss += __shfl_xor(ss, 1); ss += __shfl_xor(ss, 2); ss += __shfl_xor(ss, 4);
;             const float rstd = 1.f / sqrtf(ss * (1.f / 128.f) + EPS);
; #pragma unroll
;             for (int h = 0; h < 2; ++h) { const f32x4 a = o[2 * h] * rstd * gg[2 * h], b = o[2 * h + 1] * rstd * gg[2 * h + 1]; const v4u g8 = og[h];
;                 v4u za; za.x = pk2(a.x * bflo(g8.x), a.y * bfhi(g8.x)); za.y = pk2(a.z * bflo(g8.y), a.w * bfhi(g8.y)); za.z = pk2(b.x * bflo(g8.z), b.y * bfhi(g8.z)); za.w = pk2(b.z * bflo(g8.w), b.w * bfhi(g8.w));
;                 *(GAS v4u*)(ZA + e + 8 * h) = za; }
;         }
.LBB0_925:
	s_waitcnt vmcnt(2)
	v_lshl_add_u64 v[44:45], s[22:23], 0, v[20:21]
	v_lshl_add_u64 v[54:55], v[44:45], 0, s[98:99]
	v_mov_b32_e32 v28, v200
	v_mov_b32_e32 v29, v201
	v_mov_b32_e32 v30, v202
	v_mov_b32_e32 v31, v203
	v_mov_b32_e32 v32, v204
	v_mov_b32_e32 v33, v205
	v_mov_b32_e32 v34, v206
	v_mov_b32_e32 v35, v207
	v_mov_b32_e32 v36, v208
	v_mov_b32_e32 v37, v209
	v_mov_b32_e32 v38, v210
	v_mov_b32_e32 v39, v211
	v_mov_b32_e32 v40, v212
	v_mov_b32_e32 v41, v213
	v_mov_b32_e32 v42, v214
	v_mov_b32_e32 v43, v215
	v_mov_b32_e32 v44, v216
	v_mov_b32_e32 v45, v217
	v_mov_b32_e32 v46, v218
	v_mov_b32_e32 v47, v219
	v_mov_b32_e32 v48, v220
	v_mov_b32_e32 v49, v221
	v_mov_b32_e32 v50, v222
	v_mov_b32_e32 v51, v223
	v_add_u32_e32 v18, s10, v18
	v_cmp_lt_i32_e64 s[6:7], s40, v18
	s_or_b64 s[16:17], s[6:7], s[16:17]
	v_lshl_add_u64 v[20:21], v[20:21], 0, s[12:13]
	v_lshl_add_u64 v[22:23], v[22:23], 0, s[14:15]
	v_lshl_add_u64 v[224:225], s[22:23], 0, v[22:23]
	v_lshl_add_u64 v[224:225], v[224:225], 0, s[36:37]
	global_load_dwordx4 v[200:203], v[224:225], off offset:32
	global_load_dwordx4 v[204:207], v[224:225], off offset:16
	global_load_dwordx4 v[208:211], v[224:225], off
	global_load_dwordx4 v[212:215], v[224:225], off offset:48
	v_lshl_add_u64 v[226:227], s[22:23], 0, v[20:21]
	v_lshl_add_u64 v[226:227], v[226:227], 0, s[38:39]
	global_load_dwordx4 v[216:219], v[226:227], off
	global_load_dwordx4 v[220:223], v[226:227], off offset:16
	v_mul_f32_e32 v58, v29, v29
	v_pk_mul_f32 v[52:53], v[34:35], v[34:35]
	v_pk_mul_f32 v[56:57], v[32:33], v[32:33]
	v_mul_f32_e32 v60, v31, v31
	v_pk_mul_f32 v[62:63], v[38:39], v[38:39]
	v_pk_mul_f32 v[64:65], v[36:37], v[36:37]
	v_pk_mov_b32 v[66:67], v[56:57], v[52:53] op_sel:[1,0]
	v_mov_b32_e32 v57, v53
	v_mul_f32_e32 v68, v42, v42
	v_mul_f32_e32 v69, v43, v43
	v_pk_fma_f32 v[52:53], v[28:29], v[28:29], v[58:59] op_sel_hi:[1,1,0]
	v_pk_fma_f32 v[58:59], v[30:31], v[30:31], v[60:61] op_sel_hi:[1,1,0]
	v_pk_mov_b32 v[60:61], v[64:65], v[62:63] op_sel:[1,0]
	v_mov_b32_e32 v65, v63
	v_pk_add_f32 v[56:57], v[66:67], v[56:57]
	v_mov_b32_e32 v53, v68
	v_mov_b32_e32 v59, v69
	v_pk_add_f32 v[60:61], v[60:61], v[64:65]
	v_mul_f32_e32 v27, v40, v40
	v_mul_f32_e32 v72, v41, v41
	v_pk_add_f32 v[56:57], v[56:57], v[56:57] op_sel:[0,1] op_sel_hi:[1,0]
	v_pk_add_f32 v[52:53], v[52:53], v[58:59]
	v_pk_add_f32 v[58:59], v[60:61], v[60:61] op_sel:[0,1] op_sel_hi:[1,0]
	v_mov_b32_e32 v57, v72
	v_mov_b32_e32 v59, v27
	v_pk_add_f32 v[56:57], v[58:59], v[56:57]
	v_lshlrev_b32_e32 v62, 16, v44
	v_pk_add_f32 v[52:53], v[56:57], v[52:53]
	v_and_b32_e32 v63, 0xffff0000, v44
	v_add_f32_e32 v27, v52, v53
	ds_bpermute_b32 v52, v1, v27
	v_lshlrev_b32_e32 v44, 16, v45
	v_and_b32_e32 v45, 0xffff0000, v45
	v_lshlrev_b32_e32 v66, 16, v46
	v_and_b32_e32 v67, 0xffff0000, v46
	s_waitcnt lgkmcnt(0)
	v_add_f32_e32 v27, v27, v52
	ds_bpermute_b32 v52, v24, v27
	v_lshlrev_b32_e32 v46, 16, v47
	v_and_b32_e32 v47, 0xffff0000, v47
	v_lshlrev_b32_e32 v68, 16, v48
	v_and_b32_e32 v69, 0xffff0000, v48
	s_waitcnt lgkmcnt(0)
	v_add_f32_e32 v27, v27, v52
	ds_bpermute_b32 v52, v25, v27
	v_lshlrev_b32_e32 v48, 16, v49
	v_and_b32_e32 v49, 0xffff0000, v49
	v_lshlrev_b32_e32 v70, 16, v50
	v_and_b32_e32 v71, 0xffff0000, v50
	s_waitcnt lgkmcnt(0)
	v_add_f32_e32 v27, v27, v52
	v_fmamk_f32 v27, v27, 0x3c000000, v19
	v_mul_f32_e32 v52, 0x4f800000, v27
	v_cmp_gt_f32_e32 vcc, s11, v27
	v_lshlrev_b32_e32 v50, 16, v51
	v_and_b32_e32 v51, 0xffff0000, v51
	v_cndmask_b32_e32 v27, v27, v52, vcc
	v_sqrt_f32_e32 v52, v27
	s_nop 0
	v_add_u32_e32 v53, -1, v52
	v_add_u32_e32 v56, 1, v52
	v_fma_f32 v57, -v53, v52, v27
	v_fma_f32 v58, -v56, v52, v27
	v_cmp_ge_f32_e64 s[6:7], 0, v57
	s_nop 1
	v_cndmask_b32_e64 v52, v52, v53, s[6:7]
	v_cmp_lt_f32_e64 s[6:7], 0, v58
	s_nop 1
	v_cndmask_b32_e64 v52, v52, v56, s[6:7]
	v_mul_f32_e32 v53, 0x37800000, v52
	v_cndmask_b32_e32 v52, v52, v53, vcc
	v_cmp_class_f32_e32 vcc, v27, v26
	s_nop 1
	v_cndmask_b32_e32 v27, v52, v27, vcc
	v_div_scale_f32 v52, s[6:7], v27, v27, 1.0
	v_rcp_f32_e32 v56, v52
	v_div_scale_f32 v53, vcc, 1.0, v27, 1.0
	v_fma_f32 v57, -v52, v56, 1.0
	v_fmac_f32_e32 v56, v57, v56
	v_mul_f32_e32 v57, v53, v56
	v_fma_f32 v58, -v52, v57, v53
	v_fmac_f32_e32 v57, v58, v56
	v_fma_f32 v52, -v52, v57, v53
	v_div_fmas_f32 v52, v52, v56, v57
	v_div_fixup_f32 v52, v52, v27, 1.0
	v_pk_mul_f32 v[36:37], v[52:53], v[36:37] op_sel_hi:[0,1]
	v_pk_mul_f32 v[38:39], v[52:53], v[38:39] op_sel_hi:[0,1]
	v_pk_mul_f32 v[32:33], v[52:53], v[32:33] op_sel_hi:[0,1]
	v_pk_mul_f32 v[34:35], v[52:53], v[34:35] op_sel_hi:[0,1]
	v_pk_mul_f32 v[28:29], v[52:53], v[28:29] op_sel_hi:[0,1]
	v_pk_mul_f32 v[30:31], v[52:53], v[30:31] op_sel_hi:[0,1]
	v_pk_mul_f32 v[40:41], v[52:53], v[40:41] op_sel_hi:[0,1]
	v_pk_mul_f32 v[42:43], v[52:53], v[42:43] op_sel_hi:[0,1]
	v_pk_mul_f32 v[38:39], v[16:17], v[38:39]
	v_pk_mul_f32 v[36:37], v[14:15], v[36:37]
	v_pk_mul_f32 v[34:35], v[12:13], v[34:35]
	v_pk_mul_f32 v[32:33], v[10:11], v[32:33]
	v_pk_mul_f32 v[30:31], v[8:9], v[30:31]
	v_pk_mul_f32 v[28:29], v[6:7], v[28:29]
	v_pk_mul_f32 v[42:43], v[4:5], v[42:43]
	v_pk_mul_f32 v[40:41], v[2:3], v[40:41]
	v_pk_mul_f32 v[36:37], v[36:37], v[62:63]
	v_pk_mul_f32 v[38:39], v[38:39], v[44:45]
	v_pk_mul_f32 v[32:33], v[32:33], v[66:67]
	v_pk_mul_f32 v[34:35], v[34:35], v[46:47]
	v_pk_mul_f32 v[44:45], v[28:29], v[68:69]
	v_pk_mul_f32 v[46:47], v[30:31], v[48:49]
	v_pk_mul_f32 v[40:41], v[40:41], v[70:71]
	v_pk_mul_f32 v[42:43], v[42:43], v[50:51]
	v_cvt_pk_bf16_f32 v28, v36, v37
	v_cvt_pk_bf16_f32 v29, v38, v39
	v_cvt_pk_bf16_f32 v30, v32, v33
	v_cvt_pk_bf16_f32 v31, v34, v35
	v_cvt_pk_bf16_f32 v32, v44, v45
	v_cvt_pk_bf16_f32 v33, v46, v47
	v_cvt_pk_bf16_f32 v34, v40, v41
	v_cvt_pk_bf16_f32 v35, v42, v43
	global_store_dwordx4 v[54:55], v[28:31], off
	global_store_dwordx4 v[54:55], v[32:35], off offset:16
	s_andn2_b64 exec, exec, s[16:17]
	s_cbranch_execnz .LBB0_925
